# MLA loop: staging common path streamlined (one range test, single K1 test, 64-bit pointer bump from an SGPR constant); last three tiles via out-of-line copy
# speedup vs baseline: 1.0008x; 1.0008x over previous
; #define LAS __attribute__((address_space(3)))
; #define ATT_BAR() asm volatile("s_waitcnt lgkmcnt(0)\n\ts_barrier" ::: "memory")
; template <int DQK> __device__ __forceinline__ void x1_tile(LAS unsigned char* lds, const bf16x8 (&qf)[2][DQK / 32], const float (&m)[2], f32x4 (&s)[2][4], int fr, int fq) {
;     constexpr int NKS = DQK / 32;
; #pragma unroll
;     for (int q = 0; q < 2; ++q) { const float c = (m[q] > -1e29f) ? -m[q] : 0.f;
; #pragma unroll
;         for (int ss = 0; ss < 4; ++ss) s[q][ss] = (f32x4){c, c, c, c}; }
; #pragma unroll
;     for (int ss = 0; ss < 4; ++ss)
; #pragma unroll
;         for (int ks = 0; ks < NKS; ++ks) {
;             const bf16x8 kf = *(const LAS bf16x8*)(lds + k_off<DQK>(16 * ss + fr, 4 * ks + fq));
; #pragma unroll
;             for (int q = 0; q < 2; ++q) s[q][ss] = __builtin_amdgcn_mfma_f32_16x16x32_bf16(kf, qf[q][ks], s[q][ss], 0, 0, 0);
;         }
; }
; template <int DQK> __device__ __forceinline__ void causal_pass_pipe(LAS unsigned char* lds, const bf16* K0, int p0, const bf16* K1, int p1, const bf16* V, int pv, int thi,
;         const bf16x8 (&qf)[2][DQK / 32], const int (&tpos)[2], int wave_tmin, int wave_tmax, f32x4 (&o)[2][4], int tid) {
;     ...
;     float m[2] = {NEG, NEG}, l[2] = {0.f, 0.f};
; #pragma unroll
;     for (int i = 0; i < 2; ++i)
; #pragma unroll
;         for (int dt = 0; dt < 4; ++dt) o[i][dt] = (f32x4){0.f, 0.f, 0.f, 0.f};
;     Stage<DQK> st;
;     {
;         Stage<DQK> st1;
;         stage_load<DQK>(st, K0, p0, K1, p1, V, pv, 0, true, tid);
;         if (thi >= 1) stage_load<DQK>(st1, K0, p0, K1, p1, V, pv, 1, true, tid);
;         stage_store<DQK>(st, lds, true, tid);
;         if (thi >= 1) stage_store<DQK>(st1, lds + SLOT, true, tid);
;     }
;     ATT_BAR();
;     f32x4 sa[2][4], sb[2][4]; bool ca = true, cb = false;
;     x1_tile<DQK>(lds, qf, m, sa, fr, fq);
;     if (63 <= wave_tmin) x2_tile<true>(0, tpos, m, l, o, sa, fq); else x2_tile<false>(0, tpos, m, l, o, sa, fq);
;     int slot = 0;
.Lmla_nok1_0:
	v_mov_b32_e32 v96, 0
	v_mov_b32_e32 v97, 0
	v_mov_b32_e32 v98, 0
	v_mov_b32_e32 v99, 0
	v_mov_b32_e32 v88, 0
	v_mov_b32_e32 v89, 0
	v_mov_b32_e32 v90, 0
	v_mov_b32_e32 v91, 0
	v_mov_b32_e32 v92, 0
	v_mov_b32_e32 v93, 0
	v_mov_b32_e32 v94, 0
	v_mov_b32_e32 v95, 0
	v_mov_b32_e32 v48, 0
	v_mov_b32_e32 v49, 0
	v_mov_b32_e32 v50, 0
	v_mov_b32_e32 v51, 0
	v_mov_b32_e32 v165, 0
	v_mov_b32_e32 v200, v183
	v_mov_b32_e32 v84, 0
	v_mov_b32_e32 v85, 0
	v_mov_b32_e32 v86, 0
	v_mov_b32_e32 v87, 0
	v_mov_b32_e32 v76, 0
	v_mov_b32_e32 v77, 0
	v_mov_b32_e32 v78, 0
	v_mov_b32_e32 v79, 0
	v_mov_b32_e32 v80, 0
	v_mov_b32_e32 v81, 0
	v_mov_b32_e32 v82, 0
	v_mov_b32_e32 v83, 0
	v_mov_b32_e32 v56, 0
	v_mov_b32_e32 v57, 0
	v_mov_b32_e32 v58, 0
	v_mov_b32_e32 v59, 0
	v_mov_b32_e32 v164, 0
	v_mov_b32_e32 v211, v183
	s_mov_b32 s100, 0x20000
	s_mov_b32 s101, 0
	s_mov_b32 s98, 0x1000
	s_mov_b32 s99, 0
	v_cmp_lt_f32_e64 s[66:67], s77, v200
	v_cmp_lt_f32_e64 s[68:69], s77, v211
	s_nop 1
	v_cndmask_b32_e64 v197, 0, v200, s[66:67]
	v_cndmask_b32_e64 v198, 0, v211, s[68:69]
	s_and_b64 s[64:65], s[66:67], s[68:69]
	v_sub_f32_e32 v204, 0, v197
	v_mov_b32_e32 v205, v204
	v_mov_b32_e32 v206, v204
	v_mov_b32_e32 v207, v204
	v_sub_f32_e32 v252, 0, v198
	v_mov_b32_e32 v253, v252
	v_mov_b32_e32 v254, v252
	v_mov_b32_e32 v255, v252
	ds_read_b128 v[236:239], v199
	ds_read_b128 v[240:243], v201
	ds_read_b128 v[244:247], v210
	s_waitcnt lgkmcnt(0)
	v_mfma_f32_16x16x32_bf16 v[100:103], v[236:239], v[0:3], v[204:207]
	v_mfma_f32_16x16x32_bf16 v[116:119], v[236:239], v[12:15], v[252:255]
	v_mfma_f32_16x16x32_bf16 v[100:103], v[240:243], v[4:7], v[100:103]
	v_mfma_f32_16x16x32_bf16 v[116:119], v[240:243], v[16:19], v[116:119]
	v_mfma_f32_16x16x32_bf16 v[100:103], v[244:247], v[8:11], v[100:103]
	v_mfma_f32_16x16x32_bf16 v[116:119], v[244:247], v[20:23], v[116:119]
	ds_read_b128 v[236:239], v199 offset:4096
	ds_read_b128 v[240:243], v201 offset:4096
	ds_read_b128 v[244:247], v210 offset:4096
	s_waitcnt lgkmcnt(0)
	v_mfma_f32_16x16x32_bf16 v[104:107], v[236:239], v[0:3], v[204:207]
	v_mfma_f32_16x16x32_bf16 v[120:123], v[236:239], v[12:15], v[252:255]
	v_mfma_f32_16x16x32_bf16 v[104:107], v[240:243], v[4:7], v[104:107]
	v_mfma_f32_16x16x32_bf16 v[120:123], v[240:243], v[16:19], v[120:123]
	v_mfma_f32_16x16x32_bf16 v[104:107], v[244:247], v[8:11], v[104:107]
	v_mfma_f32_16x16x32_bf16 v[120:123], v[244:247], v[20:23], v[120:123]
	ds_read_b128 v[236:239], v199 offset:8192
	ds_read_b128 v[240:243], v201 offset:8192
	ds_read_b128 v[244:247], v210 offset:8192
	s_waitcnt lgkmcnt(0)
	v_mfma_f32_16x16x32_bf16 v[108:111], v[236:239], v[0:3], v[204:207]
	v_mfma_f32_16x16x32_bf16 v[124:127], v[236:239], v[12:15], v[252:255]
	v_mfma_f32_16x16x32_bf16 v[108:111], v[240:243], v[4:7], v[108:111]
	v_mfma_f32_16x16x32_bf16 v[124:127], v[240:243], v[16:19], v[124:127]
	v_mfma_f32_16x16x32_bf16 v[108:111], v[244:247], v[8:11], v[108:111]
	v_mfma_f32_16x16x32_bf16 v[124:127], v[244:247], v[20:23], v[124:127]
	ds_read_b128 v[236:239], v199 offset:12288
	ds_read_b128 v[240:243], v201 offset:12288
	ds_read_b128 v[244:247], v210 offset:12288
	s_waitcnt lgkmcnt(0)
	v_mfma_f32_16x16x32_bf16 v[112:115], v[236:239], v[0:3], v[204:207]
	v_mfma_f32_16x16x32_bf16 v[128:131], v[236:239], v[12:15], v[252:255]
	v_mfma_f32_16x16x32_bf16 v[112:115], v[240:243], v[4:7], v[112:115]
	v_mfma_f32_16x16x32_bf16 v[128:131], v[240:243], v[16:19], v[128:131]
	v_mfma_f32_16x16x32_bf16 v[112:115], v[244:247], v[8:11], v[112:115]
	v_mfma_f32_16x16x32_bf16 v[128:131], v[244:247], v[20:23], v[128:131]
	s_nop 7
	s_nop 7
	s_add_i32 s32, s49, 1
	s_cmp_eq_u32 s32, s9
	s_cbranch_scc1 .Lmla_mask5
	s_branch .Lmla_slow5_0
.Lmla_it0:
	s_add_i32 s96, s49, 3
	s_cmp_gt_u32 s96, s8
	s_cbranch_scc1 .Lmla_stgt0
	s_waitcnt vmcnt(0)
	ds_write_b128 v155, v[60:63] offset:53248
	ds_write_b128 v159, v[68:71] offset:53248
	v_lshl_add_u64 v[160:161], v[160:161], 0, s[100:101]
	v_lshl_add_u64 v[162:163], v[162:163], 0, s[100:101]
	global_load_dwordx4 v[60:63], v[160:161], off
	global_load_dwordx4 v[68:71], v[162:163], off
	s_cmp_eq_u32 s63, 0
	s_cbranch_scc1 .Lmla_nostage0
	ds_write_b128 v157, v[64:67] offset:53248
	v_lshl_add_u64 v[166:167], v[166:167], 0, s[98:99]
	global_load_dwordx4 v[64:67], v[166:167], off

; #define LAS __attribute__((address_space(3)))
; template <int DQK> __device__ __forceinline__ void stage_load(Stage<DQK>& s, const bf16* K0, int p0, const bf16* K1, int p1, const bf16* V, int pv, int tile, bool withV, int tid) {
;     { const int key = tid >> 3, c = tid & 7; s.k0 = *(const v4u*)(K0 + (size_t)(64 * tile + key) * p0 + 8 * c); }
;     if (DQK == 96) { if (tid < 256) { const int key = tid >> 2, c = tid & 3; s.k1 = *(const v4u*)(K1 + (size_t)(64 * tile + key) * p1 + 8 * c); } }
;     if (withV) { const int key = tid >> 3, c = tid & 7; s.v = *(const v4u*)(V + (size_t)(64 * tile + key) * pv + 8 * c); }
; }
; template <int DQK, int VO = KL<DQK>::VOFF> __device__ __forceinline__ void stage_store(const Stage<DQK>& s, LAS unsigned char* lds, bool withV, int tid) {
;     { const int key = tid >> 3, c = tid & 7; *(LAS v4u*)(lds + k_off<DQK>(key, c)) = s.k0; }
;     if (DQK == 96) { if (tid < 256) { const int key = tid >> 2, c = tid & 3; *(LAS v4u*)(lds + k_off<DQK>(key, 8 + c)) = s.k1; } }
;     if (withV) { const int key = tid >> 3, c = tid & 7; *(LAS v4u*)(lds + VO + (key * VSTR + 8 * c) * 2) = s.v; }
; }
.Lmla_it1:
	s_add_i32 s96, s49, 3
	s_cmp_gt_u32 s96, s8
	s_cbranch_scc1 .Lmla_stgt1
	s_waitcnt vmcnt(0)
	ds_write_b128 v155, v[60:63]
	ds_write_b128 v159, v[68:71]
	v_lshl_add_u64 v[160:161], v[160:161], 0, s[100:101]
	v_lshl_add_u64 v[162:163], v[162:163], 0, s[100:101]
	global_load_dwordx4 v[60:63], v[160:161], off
	global_load_dwordx4 v[68:71], v[162:163], off
	s_cmp_eq_u32 s63, 0
	s_cbranch_scc1 .Lmla_nostage1
	ds_write_b128 v157, v[64:67]
	v_lshl_add_u64 v[166:167], v[166:167], 0, s[98:99]
	global_load_dwordx4 v[64:67], v[166:167], off

; #define LAS __attribute__((address_space(3)))
; template <int DQK> __device__ __forceinline__ void stage_load(Stage<DQK>& s, const bf16* K0, int p0, const bf16* K1, int p1, const bf16* V, int pv, int tile, bool withV, int tid) {
;     { const int key = tid >> 3, c = tid & 7; s.k0 = *(const v4u*)(K0 + (size_t)(64 * tile + key) * p0 + 8 * c); }
;     if (DQK == 96) { if (tid < 256) { const int key = tid >> 2, c = tid & 3; s.k1 = *(const v4u*)(K1 + (size_t)(64 * tile + key) * p1 + 8 * c); } }
;     if (withV) { const int key = tid >> 3, c = tid & 7; s.v = *(const v4u*)(V + (size_t)(64 * tile + key) * pv + 8 * c); }
; }
; template <int DQK, int VO = KL<DQK>::VOFF> __device__ __forceinline__ void stage_store(const Stage<DQK>& s, LAS unsigned char* lds, bool withV, int tid) {
;     { const int key = tid >> 3, c = tid & 7; *(LAS v4u*)(lds + k_off<DQK>(key, c)) = s.k0; }
;     if (DQK == 96) { if (tid < 256) { const int key = tid >> 2, c = tid & 3; *(LAS v4u*)(lds + k_off<DQK>(key, 8 + c)) = s.k1; } }
;     if (withV) { const int key = tid >> 3, c = tid & 7; *(LAS v4u*)(lds + VO + (key * VSTR + 8 * c) * 2) = s.v; }
; }
.Lmla_it2:
	s_add_i32 s96, s49, 3
	s_cmp_gt_u32 s96, s8
	s_cbranch_scc1 .Lmla_stgt2
	s_waitcnt vmcnt(0)
	ds_write_b128 v155, v[60:63] offset:26624
	ds_write_b128 v159, v[68:71] offset:26624
	v_lshl_add_u64 v[160:161], v[160:161], 0, s[100:101]
	v_lshl_add_u64 v[162:163], v[162:163], 0, s[100:101]
	global_load_dwordx4 v[60:63], v[160:161], off
	global_load_dwordx4 v[68:71], v[162:163], off
	s_cmp_eq_u32 s63, 0
	s_cbranch_scc1 .Lmla_nostage2
	ds_write_b128 v157, v[64:67] offset:26624
	v_lshl_add_u64 v[166:167], v[166:167], 0, s[98:99]
	global_load_dwordx4 v[64:67], v[166:167], off

; #define LAS __attribute__((address_space(3)))
; template <int DQK> __device__ __forceinline__ void stage_load(Stage<DQK>& s, const bf16* K0, int p0, const bf16* K1, int p1, const bf16* V, int pv, int tile, bool withV, int tid) {
;     { const int key = tid >> 3, c = tid & 7; s.k0 = *(const v4u*)(K0 + (size_t)(64 * tile + key) * p0 + 8 * c); }
;     if (DQK == 96) { if (tid < 256) { const int key = tid >> 2, c = tid & 3; s.k1 = *(const v4u*)(K1 + (size_t)(64 * tile + key) * p1 + 8 * c); } }
;     if (withV) { const int key = tid >> 3, c = tid & 7; s.v = *(const v4u*)(V + (size_t)(64 * tile + key) * pv + 8 * c); }
; }
; template <int DQK, int VO = KL<DQK>::VOFF> __device__ __forceinline__ void stage_store(const Stage<DQK>& s, LAS unsigned char* lds, bool withV, int tid) {
;     { const int key = tid >> 3, c = tid & 7; *(LAS v4u*)(lds + k_off<DQK>(key, c)) = s.k0; }
;     if (DQK == 96) { if (tid < 256) { const int key = tid >> 2, c = tid & 3; *(LAS v4u*)(lds + k_off<DQK>(key, 8 + c)) = s.k1; } }
;     if (withV) { const int key = tid >> 3, c = tid & 7; *(LAS v4u*)(lds + VO + (key * VSTR + 8 * c) * 2) = s.v; }
; }
.Lmla_stgt0:
	s_add_i32 s96, s49, 2
	s_cmp_gt_u32 s96, s8
	s_cbranch_scc1 .Lmla_nostage0
	s_waitcnt vmcnt(0)
	ds_write_b128 v155, v[60:63] offset:53248
	ds_write_b128 v159, v[68:71] offset:53248
	s_cmp_eq_u32 s63, 0
	s_cbranch_scc1 .Lmla_nostage0
	ds_write_b128 v157, v[64:67] offset:53248
	s_branch .Lmla_nostage0
.Lmla_stgt1:
	s_add_i32 s96, s49, 2
	s_cmp_gt_u32 s96, s8
	s_cbranch_scc1 .Lmla_nostage1
	s_waitcnt vmcnt(0)
	ds_write_b128 v155, v[60:63]
	ds_write_b128 v159, v[68:71]
	s_cmp_eq_u32 s63, 0
	s_cbranch_scc1 .Lmla_nostage1
	ds_write_b128 v157, v[64:67]
	s_branch .Lmla_nostage1
.Lmla_stgt2:
	s_add_i32 s96, s49, 2
	s_cmp_gt_u32 s96, s8
	s_cbranch_scc1 .Lmla_nostage2
	s_waitcnt vmcnt(0)
	ds_write_b128 v155, v[60:63] offset:26624
	ds_write_b128 v159, v[68:71] offset:26624
	s_cmp_eq_u32 s63, 0
	s_cbranch_scc1 .Lmla_nostage2
	ds_write_b128 v157, v[64:67] offset:26624
	s_branch .Lmla_nostage2
